# P2 rope-table copy to LDS: four loads then one wait instead of four serial round trips
# baseline (speedup 1.0000x reference)
.LBB0_274:
	global_load_dword v4, v[0:1], off
	global_load_dword v5, v[0:1], off offset:2048
	v_lshl_add_u64 v[0:1], v[0:1], 0, s[8:9]
	v_lshl_add_u64 v[0:1], v[0:1], 0, s[8:9]
	global_load_dword v6, v[0:1], off
	global_load_dword v2, v[0:1], off offset:2048
	s_waitcnt vmcnt(0) lgkmcnt(0)
	ds_write_b32 v3, v4
	ds_write_b32 v3, v5 offset:2048
	ds_write_b32 v3, v6 offset:4096
	ds_write_b32 v3, v2 offset:6144
